# P5: three of the first four K-fragment ds_reads of each step hoisted above the C-operand set-up (first QK MFMA waits lgkmcnt(4)); on top of stack6
# speedup vs baseline: 1.0021x; 1.0021x over previous
.LBB0_1802:
	s_add_i32 s2, s83, 3
	s_add_i32 s94, s83, 2
	s_min_i32 s2, s2, s97
	s_min_i32 s3, s94, s97
	s_mul_i32 s2, s2, 0xf8000
	s_mul_i32 s3, s3, 0xf8000
	v_add_u32_e32 v2, s2, v216
	s_waitcnt vmcnt(0)
	v_add_u32_e32 v8, s3, v216
	global_load_dwordx4 v[4:7], v2, s[84:85]
	s_nop 0
	global_load_dwordx4 v[8:11], v8, s[84:85] offset:128
	ds_read_b128 v[22:25], v233 offset:9248
	ds_read_b128 v[26:29], v233 offset:13824
	ds_read_b128 v[30:33], v233 offset:13856
	s_add_i32 s2, s83, 1
	s_lshl_b32 s95, 1, s2
	v_and_b32_e32 v12, s95, v155
	v_cmp_ne_u32_e64 s[72:73], 0, v12
	s_andn2_b64 vcc, exec, s[0:1]
	s_mov_b64 s[0:1], -1
	v_cndmask_b32_e64 v130, v232, v20, s[72:73]
	v_mov_b32_e32 v131, v130
	v_mov_b32_e32 v132, v130
	v_mov_b32_e32 v133, v130
	v_mov_b32_e32 v134, v130
	v_mov_b32_e32 v135, v130
	v_mov_b32_e32 v136, v130
	v_mov_b32_e32 v137, v130
	v_mov_b32_e32 v138, v130
	v_mov_b32_e32 v139, v130
	v_mov_b32_e32 v140, v130
	v_mov_b32_e32 v141, v130
	v_mov_b32_e32 v142, v130
	v_mov_b32_e32 v143, v130
	v_mov_b32_e32 v144, v130
	v_mov_b32_e32 v145, v130
	s_cbranch_vccz .LBB0_1804
	ds_read_b128 v[12:15], v233 offset:9216
	s_mov_b64 s[0:1], 0
	s_waitcnt lgkmcnt(0)
	v_mfma_f32_32x32x16_bf16 v[66:81], v[12:15], v[206:209], v[130:145]
	ds_read_b128 v[12:15], v233 offset:13824
	s_waitcnt lgkmcnt(0)
	v_mfma_f32_32x32x16_bf16 v[82:97], v[12:15], v[206:209], v[130:145]
	ds_read_b128 v[12:15], v233 offset:9248
	s_waitcnt lgkmcnt(0)
	v_mfma_f32_32x32x16_bf16 v[66:81], v[12:15], v[202:205], v[66:81]
	ds_read_b128 v[12:15], v233 offset:13856
	s_waitcnt lgkmcnt(0)
	v_mfma_f32_32x32x16_bf16 v[82:97], v[12:15], v[202:205], v[82:97]
	ds_read_b128 v[12:15], v233 offset:9280
	s_waitcnt lgkmcnt(0)
	v_mfma_f32_32x32x16_bf16 v[66:81], v[12:15], v[198:201], v[66:81]
	ds_read_b128 v[12:15], v233 offset:13888
	s_waitcnt lgkmcnt(0)
	v_mfma_f32_32x32x16_bf16 v[82:97], v[12:15], v[198:201], v[82:97]
	ds_read_b128 v[12:15], v233 offset:9312
	s_waitcnt lgkmcnt(0)
	v_mfma_f32_32x32x16_bf16 v[66:81], v[12:15], v[194:197], v[66:81]
	ds_read_b128 v[12:15], v233 offset:13920
	s_waitcnt lgkmcnt(0)
	v_mfma_f32_32x32x16_bf16 v[82:97], v[12:15], v[194:197], v[82:97]
.LBB0_1804:
	s_andn2_b64 vcc, exec, s[0:1]
	s_cbranch_vccnz .LBB0_1807
	ds_read_b128 v[12:15], v233 offset:9216
	s_nop 5
	ds_read_b128 v[82:85], v233 offset:9280
	ds_read_b128 v[86:89], v233 offset:9312
	ds_read_b128 v[90:93], v233 offset:13888
	ds_read_b128 v[94:97], v233 offset:13920
	v_exp_f32_e32 v98, v98
	v_exp_f32_e32 v99, v99
	v_exp_f32_e32 v100, v100
	v_exp_f32_e32 v101, v101
	v_add_f32_e32 v16, 0, v98
	v_add_f32_e32 v16, v99, v16
	v_add_f32_e32 v16, v100, v16
	v_add_f32_e32 v16, v101, v16
	s_waitcnt lgkmcnt(4)
	v_mfma_f32_32x32x16_bf16 v[66:81], v[12:15], v[206:209], v[130:145]
	v_exp_f32_e32 v114, v114
	v_exp_f32_e32 v115, v115
	v_exp_f32_e32 v116, v116
	v_exp_f32_e32 v117, v117
	v_add_f32_e32 v12, v114, v16
	v_add_f32_e32 v12, v115, v12
	v_add_f32_e32 v12, v116, v12
	s_waitcnt lgkmcnt(5)
	v_mfma_f32_32x32x16_bf16 v[130:145], v[26:29], v[206:209], v[130:145]
	v_add_f32_e32 v12, v117, v12
	v_exp_f32_e32 v102, v102
	v_exp_f32_e32 v103, v103
	v_exp_f32_e32 v104, v104
	v_exp_f32_e32 v105, v105
	v_add_f32_e32 v12, v102, v12
	v_add_f32_e32 v12, v103, v12
	v_add_f32_e32 v12, v104, v12
	v_add_f32_e32 v12, v105, v12
	v_mfma_f32_32x32x16_bf16 v[66:81], v[22:25], v[202:205], v[66:81]
	v_exp_f32_e32 v118, v118
	v_exp_f32_e32 v119, v119
	v_exp_f32_e32 v120, v120
	v_exp_f32_e32 v121, v121
	v_add_f32_e32 v12, v118, v12
	v_add_f32_e32 v12, v119, v12
	v_add_f32_e32 v12, v120, v12
	s_waitcnt lgkmcnt(4)
	v_mfma_f32_32x32x16_bf16 v[130:145], v[30:33], v[202:205], v[130:145]
	v_add_f32_e32 v12, v121, v12
	v_exp_f32_e32 v106, v106
	v_exp_f32_e32 v107, v107
	v_exp_f32_e32 v108, v108
	v_exp_f32_e32 v109, v109
	v_add_f32_e32 v12, v106, v12
	v_add_f32_e32 v12, v107, v12
	v_add_f32_e32 v12, v108, v12
	v_add_f32_e32 v12, v109, v12
	s_waitcnt lgkmcnt(3)
	v_mfma_f32_32x32x16_bf16 v[66:81], v[82:85], v[198:201], v[66:81]
	v_exp_f32_e32 v122, v122
	v_exp_f32_e32 v123, v123
	v_exp_f32_e32 v124, v124
	v_exp_f32_e32 v125, v125
	v_add_f32_e32 v12, v122, v12
	v_add_f32_e32 v12, v123, v12
	v_add_f32_e32 v12, v124, v12
	s_waitcnt lgkmcnt(1)
	v_mfma_f32_32x32x16_bf16 v[130:145], v[90:93], v[198:201], v[130:145]
	v_add_f32_e32 v12, v125, v12
	v_exp_f32_e32 v110, v110
	v_exp_f32_e32 v111, v111
	v_exp_f32_e32 v112, v112
	v_exp_f32_e32 v113, v113
	v_add_f32_e32 v12, v110, v12
	v_add_f32_e32 v12, v111, v12
	v_add_f32_e32 v12, v112, v12
	v_add_f32_e32 v12, v113, v12
	v_exp_f32_e32 v126, v126
	v_mfma_f32_32x32x16_bf16 v[66:81], v[86:89], v[194:197], v[66:81]
	v_exp_f32_e32 v127, v127
	v_exp_f32_e32 v128, v128
	v_exp_f32_e32 v129, v129
	v_add_f32_e32 v12, v126, v12
	v_add_f32_e32 v12, v127, v12
	v_add_f32_e32 v12, v128, v12
	v_add_f32_e32 v15, v129, v12
	s_waitcnt lgkmcnt(0)
	v_mfma_f32_32x32x16_bf16 v[130:145], v[94:97], v[194:197], v[130:145]
	v_cmp_ngt_f32_e32 vcc, s96, v15
	s_cbranch_vccnz .LBB0_1816

.LBB0_1807:
	s_waitcnt vmcnt(3)
	ds_write_b128 v231, v[146:149]
	s_waitcnt vmcnt(2)
	ds_write_b128 v231, v[150:153] offset:27648
	s_cmp_lg_u64 s[72:73], 0
	s_waitcnt lgkmcnt(0)
	s_barrier
	s_cselect_b64 s[0:1], -1, 0
	s_cmp_eq_u64 s[72:73], 0
	v_lshl_add_u64 v[12:13], s[84:85], 0, v[2:3]
	s_cselect_b64 s[86:87], -1, 0
	s_cmp_gt_i32 s94, s97
	s_cbranch_scc1 .LBB0_1814
	s_add_i32 s0, s83, 4
	s_min_i32 s0, s0, s97
	s_mul_i32 s0, s0, 0xf8000
	v_add_u32_e32 v2, s0, v216
	global_load_dwordx4 v[146:149], v2, s[84:85]
	global_load_dwordx4 v[150:153], v[12:13], off offset:128
	ds_read_b128 v[22:25], v233 offset:32
	ds_read_b128 v[26:29], v233 offset:4608
	ds_read_b128 v[30:33], v233 offset:4640
	s_and_b32 s72, s94, 30
	s_cmp_eq_u32 s72, 0
	s_cselect_b64 vcc, -1, 0
	s_cmp_eq_u32 s83, 30
	s_cselect_b64 s[0:1], -1, 0
	s_cmp_eq_u32 s83, 62
	s_cselect_b64 s[2:3], -1, 0
	v_cndmask_b32_e64 v2, v213, v212, s[2:3]
	v_cndmask_b32_e64 v2, v2, v211, s[0:1]
	v_cndmask_b32_e32 v155, v155, v2, vcc
	v_lshrrev_b32_e32 v2, s72, v155
	v_and_b32_e32 v2, 1, v2
	v_cmp_eq_u32_e32 vcc, 1, v2
	v_bfe_u32 v12, v155, s72, 1
	v_cmp_ne_u32_e64 s[72:73], 0, v12
	v_cndmask_b32_e32 v130, v232, v20, vcc
	v_mov_b32_e32 v131, v130
	v_mov_b32_e32 v132, v130
	v_mov_b32_e32 v133, v130
	v_mov_b32_e32 v134, v130
	v_mov_b32_e32 v135, v130
	v_mov_b32_e32 v136, v130
	v_mov_b32_e32 v137, v130
	v_mov_b32_e32 v138, v130
	v_mov_b32_e32 v139, v130
	v_mov_b32_e32 v140, v130
	v_mov_b32_e32 v141, v130
	v_mov_b32_e32 v142, v130
	v_mov_b32_e32 v143, v130
	v_mov_b32_e32 v144, v130
	v_mov_b32_e32 v145, v130
	s_mov_b64 s[0:1], -1
	s_and_b64 vcc, exec, s[86:87]
	s_cbranch_vccz .LBB0_1810
	ds_read_b128 v[12:15], v233
	s_mov_b64 s[0:1], 0
	s_waitcnt lgkmcnt(0)
	v_mfma_f32_32x32x16_bf16 v[98:113], v[12:15], v[206:209], v[130:145]
	ds_read_b128 v[12:15], v233 offset:4608
	s_waitcnt lgkmcnt(0)
	v_mfma_f32_32x32x16_bf16 v[114:129], v[12:15], v[206:209], v[130:145]
	ds_read_b128 v[12:15], v233 offset:32
	s_waitcnt lgkmcnt(0)
	v_mfma_f32_32x32x16_bf16 v[98:113], v[12:15], v[202:205], v[98:113]
	ds_read_b128 v[12:15], v233 offset:4640
	s_waitcnt lgkmcnt(0)
	v_mfma_f32_32x32x16_bf16 v[114:129], v[12:15], v[202:205], v[114:129]
	ds_read_b128 v[12:15], v233 offset:64
	s_waitcnt lgkmcnt(0)
	v_mfma_f32_32x32x16_bf16 v[98:113], v[12:15], v[198:201], v[98:113]
	ds_read_b128 v[12:15], v233 offset:4672
	s_waitcnt lgkmcnt(0)
	v_mfma_f32_32x32x16_bf16 v[114:129], v[12:15], v[198:201], v[114:129]
	ds_read_b128 v[12:15], v233 offset:96
	s_waitcnt lgkmcnt(0)
	v_mfma_f32_32x32x16_bf16 v[98:113], v[12:15], v[194:197], v[98:113]
	ds_read_b128 v[12:15], v233 offset:4704
	s_waitcnt lgkmcnt(0)
	v_mfma_f32_32x32x16_bf16 v[114:129], v[12:15], v[194:197], v[114:129]
.LBB0_1810:
	s_andn2_b64 vcc, exec, s[0:1]
	s_cbranch_vccnz .LBB0_1813
	ds_read_b128 v[12:15], v233
	s_nop 5
	ds_read_b128 v[114:117], v233 offset:64
	ds_read_b128 v[118:121], v233 offset:96
	ds_read_b128 v[122:125], v233 offset:4672
	ds_read_b128 v[126:129], v233 offset:4704
	v_exp_f32_e32 v66, v66
	v_exp_f32_e32 v67, v67
	v_exp_f32_e32 v68, v68
	v_exp_f32_e32 v69, v69
	v_add_f32_e32 v2, 0, v66
	v_add_f32_e32 v2, v67, v2
	v_add_f32_e32 v2, v68, v2
	v_add_f32_e32 v2, v69, v2
	s_waitcnt lgkmcnt(4)
	v_mfma_f32_32x32x16_bf16 v[98:113], v[12:15], v[206:209], v[130:145]
	v_exp_f32_e32 v82, v82
	v_exp_f32_e32 v83, v83
	v_exp_f32_e32 v84, v84
	v_exp_f32_e32 v85, v85
	v_add_f32_e32 v2, v82, v2
	v_add_f32_e32 v2, v83, v2
	v_add_f32_e32 v2, v84, v2
	s_waitcnt lgkmcnt(5)
	v_mfma_f32_32x32x16_bf16 v[130:145], v[26:29], v[206:209], v[130:145]
	v_add_f32_e32 v2, v85, v2
	v_exp_f32_e32 v70, v70
	v_exp_f32_e32 v71, v71
	v_exp_f32_e32 v72, v72
	v_exp_f32_e32 v73, v73
	v_add_f32_e32 v2, v70, v2
	v_add_f32_e32 v2, v71, v2
	v_add_f32_e32 v2, v72, v2
	v_add_f32_e32 v2, v73, v2
	v_mfma_f32_32x32x16_bf16 v[98:113], v[22:25], v[202:205], v[98:113]
	v_exp_f32_e32 v86, v86
	v_exp_f32_e32 v87, v87
	v_exp_f32_e32 v88, v88
	v_exp_f32_e32 v89, v89
	v_add_f32_e32 v2, v86, v2
	v_add_f32_e32 v2, v87, v2
	v_add_f32_e32 v2, v88, v2
	s_waitcnt lgkmcnt(4)
	v_mfma_f32_32x32x16_bf16 v[130:145], v[30:33], v[202:205], v[130:145]
	v_add_f32_e32 v2, v89, v2
	v_exp_f32_e32 v74, v74
	v_exp_f32_e32 v75, v75
	v_exp_f32_e32 v76, v76
	v_exp_f32_e32 v77, v77
	v_add_f32_e32 v2, v74, v2
	v_add_f32_e32 v2, v75, v2
	v_add_f32_e32 v2, v76, v2
	v_add_f32_e32 v2, v77, v2
	s_waitcnt lgkmcnt(3)
	v_mfma_f32_32x32x16_bf16 v[98:113], v[114:117], v[198:201], v[98:113]
	v_exp_f32_e32 v90, v90
	v_exp_f32_e32 v91, v91
	v_exp_f32_e32 v92, v92
	v_exp_f32_e32 v93, v93
	v_add_f32_e32 v2, v90, v2
	v_add_f32_e32 v2, v91, v2
	v_add_f32_e32 v2, v92, v2
	s_waitcnt lgkmcnt(1)
	v_mfma_f32_32x32x16_bf16 v[130:145], v[122:125], v[198:201], v[130:145]
	v_add_f32_e32 v2, v93, v2
	v_exp_f32_e32 v78, v78
	v_exp_f32_e32 v79, v79
	v_exp_f32_e32 v80, v80
	v_exp_f32_e32 v81, v81
	v_add_f32_e32 v2, v78, v2
	v_add_f32_e32 v2, v79, v2
	v_add_f32_e32 v2, v80, v2
	v_add_f32_e32 v2, v81, v2
	v_exp_f32_e32 v94, v94
	v_mfma_f32_32x32x16_bf16 v[98:113], v[118:121], v[194:197], v[98:113]
	v_exp_f32_e32 v95, v95
	v_exp_f32_e32 v96, v96
	v_exp_f32_e32 v97, v97
	v_add_f32_e32 v2, v94, v2
	v_add_f32_e32 v2, v95, v2
	v_add_f32_e32 v2, v96, v2
	v_add_f32_e32 v15, v97, v2
	s_waitcnt lgkmcnt(0)
	v_mfma_f32_32x32x16_bf16 v[130:145], v[126:129], v[194:197], v[130:145]
	v_cmp_ngt_f32_e32 vcc, s96, v15
	s_cbranch_vccnz .LBB0_1817
